# P6 attention epilogue: gate SiLU and output scaling multiplies as packed f32 multiplies (bit-identical per element)
# baseline (speedup 1.0000x reference)
; __device__ __forceinline__ void attn_phase(const Ptrs& P, int gw, int NGW, int lane) {
;     ...
;             bf16x8 k3[4], v2[2][2];
;             { const int t3 = kt > 2 ? kt - 3 : 0, t2 = kt > 1 ? kt - 2 : 0;
; #pragma unroll
;               for (int ks = 0; ks < 4; ++ks) k3[ks] = kbase[(size_t)t3 * 256 + ks * 64];
; #pragma unroll
;               for (int dt = 0; dt < 2; ++dt)
; #pragma unroll
;                   for (int s = 0; s < 2; ++s) v2[dt][s] = vbase[(size_t)t2 * 256 + (dt * 2 + s) * 64]; }
;             f32x16 sa;
; #pragma unroll
;             for (int i = 0; i < 16; ++i) sa[i] = 0.f;
; #pragma unroll
;             for (int ks = 0; ks < 4; ++ks) sa = MFMA32(kf[ks], qf[ks], sa);
;             float beta[16], f[16];
;             const bool diag = (kt == qt);
; #pragma unroll
;             for (int i = 0; i < 16; ++i) { float ff = rcpf_(1.0f + ex2(sa[i])), bt = 1.0f - ff;
;                 if (diag) { const bool valid = crow(i, hh) < r; bt = valid ? bt : 0.0f; ff = valid ? ff : 1.0f; }
;                 beta[i] = bt; f[i] = ff; }
;             float gp[4], ot[4], pr[4];
; #pragma unroll
;             for (int g = 0; g < 4; ++g) { gp[g] = (f[4 * g] * f[4 * g + 1]) * (f[4 * g + 2] * f[4 * g + 3]);
;                 const auto rr = __builtin_amdgcn_permlane32_swap(__float_as_uint(gp[g]), __float_as_uint(gp[g]), false, false);
;                 ot[g] = __uint_as_float(rr[1]); pr[g] = __uint_as_float(rr[0]) * __uint_as_float(rr[1]); }
;             float suf = Pc; float att[16];
; #pragma unroll
;             for (int g = 3; g >= 0; --g) { float p = (hh == 0) ? suf * ot[g] : suf;
;                 att[4 * g + 3] = beta[4 * g + 3] * p; p *= f[4 * g + 3];
;                 att[4 * g + 2] = beta[4 * g + 2] * p; p *= f[4 * g + 2];
;                 att[4 * g + 1] = beta[4 * g + 1] * p; p *= f[4 * g + 1];
;                 att[4 * g] = beta[4 * g] * p;
;                 suf *= pr[g]; }
;             Pc = suf;
; #pragma unroll
;             for (int i = 0; i < 16; ++i) asm("" : "+v"(att[i]));
;             bf16x8 pf[2];
; #pragma unroll
;             for (int s = 0; s < 2; ++s) { v4u t; t.x = pk2(att[8 * s], att[8 * s + 1]); t.y = pk2(att[8 * s + 2], att[8 * s + 3]); t.z = pk2(att[8 * s + 4], att[8 * s + 5]); t.w = pk2(att[8 * s + 6], att[8 * s + 7]); pf[s] = __builtin_bit_cast(bf16x8, t); }
; #pragma unroll
.Lp6_unit:
	s_mov_b32 s68, s63
	v_mov_b32_e32 v229, 1.0
	v_mov_b32_e32 v252, 1.0
	v_mov_b32_e32 v253, 0xbfb8aa3b
	s_waitcnt vmcnt(20)
	v_mfma_f32_32x32x16_bf16 v[32:47], v[64:67], v[48:51], 0
	v_mfma_f32_32x32x16_bf16 v[32:47], v[68:71], v[52:55], v[32:47]
	v_mfma_f32_32x32x16_bf16 v[32:47], v[72:75], v[56:59], v[32:47]
	v_mfma_f32_32x32x16_bf16 v[32:47], v[76:79], v[60:63], v[32:47]
	s_sub_i32 s80, s68, 3
	s_max_i32 s80, s80, 0
	s_lshl_b32 s80, s80, 12
	s_add_u32 s74, s70, s80
	s_addc_u32 s75, s71, 0
	s_add_u32 s76, s72, s80
	s_addc_u32 s77, s73, 0
	s_nop 4
	v_exp_f32_e32 v32, v32
	v_exp_f32_e32 v33, v33
	v_exp_f32_e32 v34, v34
	v_exp_f32_e32 v35, v35
	v_exp_f32_e32 v36, v36
	v_exp_f32_e32 v37, v37
	v_exp_f32_e32 v38, v38
	v_exp_f32_e32 v39, v39
	v_exp_f32_e32 v40, v40
	v_exp_f32_e32 v41, v41
	v_exp_f32_e32 v42, v42
	v_exp_f32_e32 v43, v43
	v_exp_f32_e32 v44, v44
	v_exp_f32_e32 v45, v45
	v_exp_f32_e32 v46, v46
	v_exp_f32_e32 v47, v47
	v_pk_add_f32 v[32:33], v[32:33], v[252:253] op_sel_hi:[1,0]
	v_pk_add_f32 v[34:35], v[34:35], v[252:253] op_sel_hi:[1,0]
	v_pk_add_f32 v[36:37], v[36:37], v[252:253] op_sel_hi:[1,0]
	v_pk_add_f32 v[38:39], v[38:39], v[252:253] op_sel_hi:[1,0]
	v_pk_add_f32 v[40:41], v[40:41], v[252:253] op_sel_hi:[1,0]
	v_pk_add_f32 v[42:43], v[42:43], v[252:253] op_sel_hi:[1,0]
	v_pk_add_f32 v[44:45], v[44:45], v[252:253] op_sel_hi:[1,0]
	v_pk_add_f32 v[46:47], v[46:47], v[252:253] op_sel_hi:[1,0]
	v_rcp_f32_e32 v32, v32
	v_rcp_f32_e32 v33, v33
	v_rcp_f32_e32 v34, v34
	v_rcp_f32_e32 v35, v35
	v_rcp_f32_e32 v36, v36
	v_rcp_f32_e32 v37, v37
	v_rcp_f32_e32 v38, v38
	v_rcp_f32_e32 v39, v39
	v_rcp_f32_e32 v40, v40
	v_rcp_f32_e32 v41, v41
	v_rcp_f32_e32 v42, v42
	v_rcp_f32_e32 v43, v43
	v_rcp_f32_e32 v44, v44
	v_rcp_f32_e32 v45, v45
	v_rcp_f32_e32 v46, v46
	v_rcp_f32_e32 v47, v47
	v_cndmask_b32_e64 v32, 1.0, v32, s[4:5]
	v_cndmask_b32_e64 v33, 1.0, v33, s[6:7]
	v_cndmask_b32_e64 v34, 1.0, v34, s[8:9]
	v_cndmask_b32_e64 v35, 1.0, v35, s[10:11]
	v_cndmask_b32_e64 v36, 1.0, v36, s[12:13]
	v_cndmask_b32_e64 v37, 1.0, v37, s[14:15]
	v_cndmask_b32_e64 v38, 1.0, v38, s[16:17]
	v_cndmask_b32_e64 v39, 1.0, v39, s[18:19]
	v_cndmask_b32_e64 v40, 1.0, v40, s[20:21]
	v_cndmask_b32_e64 v41, 1.0, v41, s[22:23]
	v_cndmask_b32_e64 v42, 1.0, v42, s[24:25]
	v_cndmask_b32_e64 v43, 1.0, v43, s[26:27]
	v_cndmask_b32_e64 v44, 1.0, v44, s[28:29]
	v_cndmask_b32_e64 v45, 1.0, v45, s[30:31]
	v_cndmask_b32_e64 v46, 1.0, v46, s[34:35]
	v_cndmask_b32_e64 v47, 1.0, v47, s[36:37]
	v_pk_mul_f32 v[230:231], v[32:33], v[34:35]
	v_mul_f32_e32 v219, v230, v231
	v_pk_mul_f32 v[230:231], v[36:37], v[38:39]
	v_mul_f32_e32 v220, v230, v231
	v_pk_mul_f32 v[230:231], v[40:41], v[42:43]
	v_mul_f32_e32 v221, v230, v231
	v_pk_mul_f32 v[230:231], v[44:45], v[46:47]
	v_mul_f32_e32 v222, v230, v231
	v_mov_b32_e32 v223, v219
	v_mov_b32_e32 v224, v220
	v_mov_b32_e32 v225, v221
	v_mov_b32_e32 v226, v222
	s_nop 1
	v_permlane32_swap_b32_e32 v219, v223
	v_permlane32_swap_b32_e32 v220, v224
	v_permlane32_swap_b32_e32 v221, v225
	v_permlane32_swap_b32_e32 v222, v226
	v_mul_f32_e32 v228, v229, v226
	v_cndmask_b32_e64 v228, v229, v228, s[2:3]
	v_mul_f32_e32 v230, v228, v47
	v_sub_f32_e32 v218, v228, v230
	v_mul_f32_e32 v228, v230, v46
	v_sub_f32_e32 v217, v230, v228
	v_mul_f32_e32 v230, v228, v45
	v_sub_f32_e32 v216, v228, v230
	v_mul_f32_e32 v228, v230, v44
	v_sub_f32_e32 v215, v230, v228
	v_mul_f32_e32 v227, v222, v226
	v_mul_f32_e32 v229, v229, v227
	v_mul_f32_e32 v228, v229, v225
	v_cndmask_b32_e64 v228, v229, v228, s[2:3]
	v_mul_f32_e32 v230, v228, v43
	v_sub_f32_e32 v214, v228, v230
	v_mul_f32_e32 v228, v230, v42
	v_sub_f32_e32 v213, v230, v228
	v_mul_f32_e32 v230, v228, v41
	v_sub_f32_e32 v212, v228, v230
	v_mul_f32_e32 v228, v230, v40
	v_sub_f32_e32 v211, v230, v228
	v_mul_f32_e32 v227, v221, v225
	v_mul_f32_e32 v229, v229, v227
	v_mul_f32_e32 v228, v229, v224
	v_cndmask_b32_e64 v228, v229, v228, s[2:3]
	v_mul_f32_e32 v230, v228, v39
	v_sub_f32_e32 v210, v228, v230
	v_mul_f32_e32 v228, v230, v38
	v_sub_f32_e32 v209, v230, v228
	v_mul_f32_e32 v230, v228, v37
	v_sub_f32_e32 v208, v228, v230
	v_mul_f32_e32 v228, v230, v36
	v_sub_f32_e32 v207, v230, v228
	v_mul_f32_e32 v227, v220, v224
	v_mul_f32_e32 v229, v229, v227
	v_mul_f32_e32 v228, v229, v223
	v_cndmask_b32_e64 v228, v229, v228, s[2:3]
	v_mul_f32_e32 v230, v228, v35
	v_sub_f32_e32 v206, v228, v230
	v_mul_f32_e32 v228, v230, v34
	v_sub_f32_e32 v205, v230, v228
	v_mul_f32_e32 v230, v228, v33
	v_sub_f32_e32 v204, v228, v230
	v_mul_f32_e32 v228, v230, v32
	v_sub_f32_e32 v203, v230, v228
	v_mul_f32_e32 v227, v219, v223
	v_mul_f32_e32 v229, v229, v227
	v_cvt_pk_bf16_f32 v176, v203, v204
	v_cvt_pk_bf16_f32 v177, v205, v206
	v_cvt_pk_bf16_f32 v178, v207, v208
	v_cvt_pk_bf16_f32 v179, v209, v210
	v_cvt_pk_bf16_f32 v180, v211, v212
	v_cvt_pk_bf16_f32 v181, v213, v214
	v_cvt_pk_bf16_f32 v182, v215, v216
	v_cvt_pk_bf16_f32 v183, v217, v218
	v_cmp_nge_f32_e32 vcc, 0x8000, v229
	s_waitcnt vmcnt(16)
	s_nop 0
	v_mfma_f32_32x32x16_bf16 v[0:15], v[80:83], v[176:179], 0
	v_mfma_f32_32x32x16_bf16 v[16:31], v[88:91], v[176:179], 0
	v_mfma_f32_32x32x16_bf16 v[0:15], v[84:87], v[180:183], v[0:15]
	v_mfma_f32_32x32x16_bf16 v[16:31], v[92:95], v[180:183], v[16:31]
	s_cmp_eq_u64 vcc, 0
	s_cbranch_scc1 .Lp6_epi
	s_cmp_eq_u32 s68, 0
	s_cbranch_scc1 .Lp6_epi
	s_add_i32 s68, s68, -1
	global_load_dwordx4 v[64:67], v185, s[74:75]
	global_load_dwordx4 v[68:71], v185, s[74:75] offset:1024
	global_load_dwordx4 v[72:75], v185, s[74:75] offset:2048
	global_load_dwordx4 v[76:79], v185, s[74:75] offset:3072
	global_load_dwordx4 v[80:83], v185, s[76:77]
	global_load_dwordx4 v[84:87], v185, s[76:77] offset:1024
	global_load_dwordx4 v[88:91], v185, s[76:77] offset:2048
	global_load_dwordx4 v[92:95], v185, s[76:77] offset:3072

; __device__ __forceinline__ unsigned pk2(float lo, float hi) { f32x2_t v = {lo, hi}; bf16x2_t b = __builtin_convertvector(v, bf16x2_t); return __builtin_bit_cast(unsigned, b); }
; __device__ __forceinline__ float bflo(unsigned u) { return __uint_as_float(u << 16); }
; __device__ __forceinline__ float bfhi(unsigned u) { return __uint_as_float(u & 0xffff0000u); }
; __device__ __forceinline__ float sigmoid_(float x) { return rcpf_(1.0f + ex2(-LOG2E * x)); }
; __device__ __forceinline__ void attn_phase(const Ptrs& P, int gw, int NGW, int lane) {
;     ...
;         const size_t row = rowbase + qt * 32 + r;
;         bf16* op = OG + row * AW + h * HD + 8 * hh;
; #pragma unroll
;         for (int dt = 0; dt < 2; ++dt)
; #pragma unroll
;             for (int g = 0; g < 4; g += 2) { v2u pk[2];
; #pragma unroll
;                 for (int e = 0; e < 2; ++e) { const v2u graw = gq_[dt * 4 + g + e]; const int i0 = 4 * (g + e);
;                     const float g0 = bflo(graw.x), g1 = bfhi(graw.x), g2 = bflo(graw.y), g3 = bfhi(graw.y);
;                     const float v0 = dt ? o1[i0] : o0[i0], v1 = dt ? o1[i0 + 1] : o0[i0 + 1], v2 = dt ? o1[i0 + 2] : o0[i0 + 2], v3 = dt ? o1[i0 + 3] : o0[i0 + 3];
;                     float w0 = v0 * (g0 * sigmoid_(g0)), w1 = v1 * (g1 * sigmoid_(g1)), w2 = v2 * (g2 * sigmoid_(g2)), w3 = v3 * (g3 * sigmoid_(g3));
;                     asm("" : "+v"(w0)); asm("" : "+v"(w1)); asm("" : "+v"(w2)); asm("" : "+v"(w3));
;                     pk[e].x = pk2(w0, w1); pk[e].y = pk2(w2, w3); }
;                 const auto rx = __builtin_amdgcn_permlane32_swap(pk[0].x, pk[1].x, false, false), ry = __builtin_amdgcn_permlane32_swap(pk[0].y, pk[1].y, false, false);
;                 const v4u o = {rx[0], ry[0], rx[1], ry[1]};
;                 *(v4u*)(op + dt * 32 + 8 * g) = o; }
.Lp6_epi_compute:
	v_lshlrev_b32_e32 v240, 16, v187
	v_and_b32_e32 v241, 0xffff0000, v187
	v_lshlrev_b32_e32 v242, 16, v188
	v_and_b32_e32 v243, 0xffff0000, v188
	v_pk_mul_f32 v[244:245], v[240:241], v[252:253] op_sel:[0,1] op_sel_hi:[1,1]
	v_pk_mul_f32 v[246:247], v[242:243], v[252:253] op_sel:[0,1] op_sel_hi:[1,1]
	v_exp_f32_e32 v244, v244
	v_exp_f32_e32 v245, v245
	v_exp_f32_e32 v246, v246
	v_exp_f32_e32 v247, v247
	v_pk_add_f32 v[244:245], v[244:245], v[252:253] op_sel_hi:[1,0]
	v_pk_add_f32 v[246:247], v[246:247], v[252:253] op_sel_hi:[1,0]
	v_rcp_f32_e32 v244, v244
	v_rcp_f32_e32 v245, v245
	v_rcp_f32_e32 v246, v246
	v_rcp_f32_e32 v247, v247
	v_pk_mul_f32 v[240:241], v[244:245], v[240:241]
	v_pk_mul_f32 v[242:243], v[246:247], v[242:243]
	v_pk_mul_f32 v[240:241], v[240:241], v[0:1]
	v_pk_mul_f32 v[242:243], v[242:243], v[2:3]
	v_cvt_pk_bf16_f32 v248, v240, v241
	v_cvt_pk_bf16_f32 v249, v242, v243
	v_lshlrev_b32_e32 v240, 16, v189
	v_and_b32_e32 v241, 0xffff0000, v189
	v_lshlrev_b32_e32 v242, 16, v190
	v_and_b32_e32 v243, 0xffff0000, v190
	v_pk_mul_f32 v[244:245], v[240:241], v[252:253] op_sel:[0,1] op_sel_hi:[1,1]
	v_pk_mul_f32 v[246:247], v[242:243], v[252:253] op_sel:[0,1] op_sel_hi:[1,1]
	v_exp_f32_e32 v244, v244
	v_exp_f32_e32 v245, v245
	v_exp_f32_e32 v246, v246
	v_exp_f32_e32 v247, v247
	v_pk_add_f32 v[244:245], v[244:245], v[252:253] op_sel_hi:[1,0]
	v_pk_add_f32 v[246:247], v[246:247], v[252:253] op_sel_hi:[1,0]
	v_rcp_f32_e32 v244, v244
	v_rcp_f32_e32 v245, v245
	v_rcp_f32_e32 v246, v246
	v_rcp_f32_e32 v247, v247
	v_pk_mul_f32 v[240:241], v[244:245], v[240:241]
	v_pk_mul_f32 v[242:243], v[246:247], v[242:243]
	v_pk_mul_f32 v[240:241], v[240:241], v[4:5]
	v_pk_mul_f32 v[242:243], v[242:243], v[6:7]
	v_cvt_pk_bf16_f32 v250, v240, v241
	v_cvt_pk_bf16_f32 v251, v242, v243
	s_nop 1
	v_permlane32_swap_b32_e32 v248, v250
	v_permlane32_swap_b32_e32 v249, v251
	global_store_dwordx4 v239, v[248:251], s[42:43]
	s_nop 1
	v_lshlrev_b32_e32 v240, 16, v191
	v_and_b32_e32 v241, 0xffff0000, v191
	v_lshlrev_b32_e32 v242, 16, v192
	v_and_b32_e32 v243, 0xffff0000, v192
	v_pk_mul_f32 v[244:245], v[240:241], v[252:253] op_sel:[0,1] op_sel_hi:[1,1]
	v_pk_mul_f32 v[246:247], v[242:243], v[252:253] op_sel:[0,1] op_sel_hi:[1,1]
	v_exp_f32_e32 v244, v244
	v_exp_f32_e32 v245, v245
	v_exp_f32_e32 v246, v246
	v_exp_f32_e32 v247, v247
	v_pk_add_f32 v[244:245], v[244:245], v[252:253] op_sel_hi:[1,0]
	v_pk_add_f32 v[246:247], v[246:247], v[252:253] op_sel_hi:[1,0]
	v_rcp_f32_e32 v244, v244
	v_rcp_f32_e32 v245, v245
	v_rcp_f32_e32 v246, v246
	v_rcp_f32_e32 v247, v247
	v_pk_mul_f32 v[240:241], v[244:245], v[240:241]
	v_pk_mul_f32 v[242:243], v[246:247], v[242:243]
	v_pk_mul_f32 v[240:241], v[240:241], v[8:9]
	v_pk_mul_f32 v[242:243], v[242:243], v[10:11]
	v_cvt_pk_bf16_f32 v248, v240, v241
	v_cvt_pk_bf16_f32 v249, v242, v243
	v_lshlrev_b32_e32 v240, 16, v193
	v_and_b32_e32 v241, 0xffff0000, v193
	v_lshlrev_b32_e32 v242, 16, v194
	v_and_b32_e32 v243, 0xffff0000, v194
	v_pk_mul_f32 v[244:245], v[240:241], v[252:253] op_sel:[0,1] op_sel_hi:[1,1]
	v_pk_mul_f32 v[246:247], v[242:243], v[252:253] op_sel:[0,1] op_sel_hi:[1,1]
	v_exp_f32_e32 v244, v244
	v_exp_f32_e32 v245, v245
	v_exp_f32_e32 v246, v246
	v_exp_f32_e32 v247, v247
	v_pk_add_f32 v[244:245], v[244:245], v[252:253] op_sel_hi:[1,0]
	v_pk_add_f32 v[246:247], v[246:247], v[252:253] op_sel_hi:[1,0]
	v_rcp_f32_e32 v244, v244
	v_rcp_f32_e32 v245, v245
	v_rcp_f32_e32 v246, v246
	v_rcp_f32_e32 v247, v247
	v_pk_mul_f32 v[240:241], v[244:245], v[240:241]
	v_pk_mul_f32 v[242:243], v[246:247], v[242:243]
	v_pk_mul_f32 v[240:241], v[240:241], v[12:13]
	v_pk_mul_f32 v[242:243], v[242:243], v[14:15]
	v_cvt_pk_bf16_f32 v250, v240, v241
	v_cvt_pk_bf16_f32 v251, v242, v243
	s_nop 1
	v_permlane32_swap_b32_e32 v248, v250
	v_permlane32_swap_b32_e32 v249, v251
	global_store_dwordx4 v239, v[248:251], s[42:43] offset:32
	s_nop 1
	v_lshlrev_b32_e32 v240, 16, v195
; __device__ __forceinline__ unsigned pk2(float lo, float hi) { f32x2_t v = {lo, hi}; bf16x2_t b = __builtin_convertvector(v, bf16x2_t); return __builtin_bit_cast(unsigned, b); }
; __device__ __forceinline__ float bflo(unsigned u) { return __uint_as_float(u << 16); }
; __device__ __forceinline__ float bfhi(unsigned u) { return __uint_as_float(u & 0xffff0000u); }
; __device__ __forceinline__ float sigmoid_(float x) { return rcpf_(1.0f + ex2(-LOG2E * x)); }
; __device__ __forceinline__ void attn_phase(const Ptrs& P, int gw, int NGW, int lane) {
;     ...
; #pragma unroll
;         for (int dt = 0; dt < 2; ++dt)
; #pragma unroll
;             for (int g = 0; g < 4; g += 2) { v2u pk[2];
; #pragma unroll
;                 for (int e = 0; e < 2; ++e) { const v2u graw = gq_[dt * 4 + g + e]; const int i0 = 4 * (g + e);
;                     const float g0 = bflo(graw.x), g1 = bfhi(graw.x), g2 = bflo(graw.y), g3 = bfhi(graw.y);
;                     const float v0 = dt ? o1[i0] : o0[i0], v1 = dt ? o1[i0 + 1] : o0[i0 + 1], v2 = dt ? o1[i0 + 2] : o0[i0 + 2], v3 = dt ? o1[i0 + 3] : o0[i0 + 3];
;                     float w0 = v0 * (g0 * sigmoid_(g0)), w1 = v1 * (g1 * sigmoid_(g1)), w2 = v2 * (g2 * sigmoid_(g2)), w3 = v3 * (g3 * sigmoid_(g3));
;                     asm("" : "+v"(w0)); asm("" : "+v"(w1)); asm("" : "+v"(w2)); asm("" : "+v"(w3));
;                     pk[e].x = pk2(w0, w1); pk[e].y = pk2(w2, w3); }
;                 const auto rx = __builtin_amdgcn_permlane32_swap(pk[0].x, pk[1].x, false, false), ry = __builtin_amdgcn_permlane32_swap(pk[0].y, pk[1].y, false, false);
;                 const v4u o = {rx[0], ry[0], rx[1], ry[1]};
;                 *(v4u*)(op + dt * 32 + 8 * g) = o; }
	v_and_b32_e32 v241, 0xffff0000, v195
	v_lshlrev_b32_e32 v242, 16, v196
	v_and_b32_e32 v243, 0xffff0000, v196
	v_pk_mul_f32 v[244:245], v[240:241], v[252:253] op_sel:[0,1] op_sel_hi:[1,1]
	v_pk_mul_f32 v[246:247], v[242:243], v[252:253] op_sel:[0,1] op_sel_hi:[1,1]
	v_exp_f32_e32 v244, v244
	v_exp_f32_e32 v245, v245
	v_exp_f32_e32 v246, v246
	v_exp_f32_e32 v247, v247
	v_pk_add_f32 v[244:245], v[244:245], v[252:253] op_sel_hi:[1,0]
	v_pk_add_f32 v[246:247], v[246:247], v[252:253] op_sel_hi:[1,0]
	v_rcp_f32_e32 v244, v244
	v_rcp_f32_e32 v245, v245
	v_rcp_f32_e32 v246, v246
	v_rcp_f32_e32 v247, v247
	v_pk_mul_f32 v[240:241], v[244:245], v[240:241]
	v_pk_mul_f32 v[242:243], v[246:247], v[242:243]
	v_pk_mul_f32 v[240:241], v[240:241], v[16:17]
	v_pk_mul_f32 v[242:243], v[242:243], v[18:19]
	v_cvt_pk_bf16_f32 v248, v240, v241
	v_cvt_pk_bf16_f32 v249, v242, v243
	v_lshlrev_b32_e32 v240, 16, v197
	v_and_b32_e32 v241, 0xffff0000, v197
	v_lshlrev_b32_e32 v242, 16, v198
	v_and_b32_e32 v243, 0xffff0000, v198
	v_pk_mul_f32 v[244:245], v[240:241], v[252:253] op_sel:[0,1] op_sel_hi:[1,1]
	v_pk_mul_f32 v[246:247], v[242:243], v[252:253] op_sel:[0,1] op_sel_hi:[1,1]
	v_exp_f32_e32 v244, v244
	v_exp_f32_e32 v245, v245
	v_exp_f32_e32 v246, v246
	v_exp_f32_e32 v247, v247
	v_pk_add_f32 v[244:245], v[244:245], v[252:253] op_sel_hi:[1,0]
	v_pk_add_f32 v[246:247], v[246:247], v[252:253] op_sel_hi:[1,0]
	v_rcp_f32_e32 v244, v244
	v_rcp_f32_e32 v245, v245
	v_rcp_f32_e32 v246, v246
	v_rcp_f32_e32 v247, v247
	v_pk_mul_f32 v[240:241], v[244:245], v[240:241]
	v_pk_mul_f32 v[242:243], v[246:247], v[242:243]
	v_pk_mul_f32 v[240:241], v[240:241], v[20:21]
	v_pk_mul_f32 v[242:243], v[242:243], v[22:23]
	v_cvt_pk_bf16_f32 v250, v240, v241
	v_cvt_pk_bf16_f32 v251, v242, v243
	s_nop 1
	v_permlane32_swap_b32_e32 v248, v250
	v_permlane32_swap_b32_e32 v249, v251
	global_store_dwordx4 v239, v[248:251], s[42:43] offset:64
	s_nop 1
	v_lshlrev_b32_e32 v240, 16, v199
	v_and_b32_e32 v241, 0xffff0000, v199
	v_lshlrev_b32_e32 v242, 16, v200
	v_and_b32_e32 v243, 0xffff0000, v200
	v_pk_mul_f32 v[244:245], v[240:241], v[252:253] op_sel:[0,1] op_sel_hi:[1,1]
	v_pk_mul_f32 v[246:247], v[242:243], v[252:253] op_sel:[0,1] op_sel_hi:[1,1]
	v_exp_f32_e32 v244, v244
	v_exp_f32_e32 v245, v245
	v_exp_f32_e32 v246, v246
	v_exp_f32_e32 v247, v247
	v_pk_add_f32 v[244:245], v[244:245], v[252:253] op_sel_hi:[1,0]
	v_pk_add_f32 v[246:247], v[246:247], v[252:253] op_sel_hi:[1,0]
	v_rcp_f32_e32 v244, v244
	v_rcp_f32_e32 v245, v245
	v_rcp_f32_e32 v246, v246
	v_rcp_f32_e32 v247, v247
	v_pk_mul_f32 v[240:241], v[244:245], v[240:241]
	v_pk_mul_f32 v[242:243], v[246:247], v[242:243]
	v_pk_mul_f32 v[240:241], v[240:241], v[24:25]
	v_pk_mul_f32 v[242:243], v[242:243], v[26:27]
	v_cvt_pk_bf16_f32 v248, v240, v241
	v_cvt_pk_bf16_f32 v249, v242, v243
	v_lshlrev_b32_e32 v240, 16, v201
	v_and_b32_e32 v241, 0xffff0000, v201
	v_lshlrev_b32_e32 v242, 16, v202
	v_and_b32_e32 v243, 0xffff0000, v202
	v_pk_mul_f32 v[244:245], v[240:241], v[252:253] op_sel:[0,1] op_sel_hi:[1,1]
	v_pk_mul_f32 v[246:247], v[242:243], v[252:253] op_sel:[0,1] op_sel_hi:[1,1]
	v_exp_f32_e32 v244, v244
	v_exp_f32_e32 v245, v245
	v_exp_f32_e32 v246, v246
	v_exp_f32_e32 v247, v247
	v_pk_add_f32 v[244:245], v[244:245], v[252:253] op_sel_hi:[1,0]
	v_pk_add_f32 v[246:247], v[246:247], v[252:253] op_sel_hi:[1,0]
	v_rcp_f32_e32 v244, v244
	v_rcp_f32_e32 v245, v245
	v_rcp_f32_e32 v246, v246
	v_rcp_f32_e32 v247, v247
	v_pk_mul_f32 v[240:241], v[244:245], v[240:241]
	v_pk_mul_f32 v[242:243], v[246:247], v[242:243]
	v_pk_mul_f32 v[240:241], v[240:241], v[28:29]
	v_pk_mul_f32 v[242:243], v[242:243], v[30:31]
	v_cvt_pk_bf16_f32 v250, v240, v241
	v_cvt_pk_bf16_f32 v251, v242, v243
	s_nop 1
	v_permlane32_swap_b32_e32 v248, v250
	v_permlane32_swap_b32_e32 v249, v251
	global_store_dwordx4 v239, v[248:251], s[42:43] offset:96
	s_nop 1
	s_cmp_lg_u32 s82, 0
	s_cbranch_scc1 .Lp6_unit
